# v108 plus s_setprio 1/0 around the MFMA groups of the attention loops (now that their VALU share is smaller)
# speedup vs baseline: 1.0060x; 1.0009x over previous
.LBB0_684:
	v_pk_fma_f32 v[2:3], v[80:81], s[8:9], v[198:199] op_sel_hi:[1,0,0] neg_lo:[0,0,1] neg_hi:[0,0,1]
	v_lshl_add_u32 v0, s38, 6, v211
	v_exp_f32_e32 v14, v2
	v_exp_f32_e32 v15, v3
	v_pk_fma_f32 v[2:3], v[82:83], s[8:9], v[198:199] op_sel_hi:[1,0,0] neg_lo:[0,0,1] neg_hi:[0,0,1]
	v_pk_fma_f32 v[6:7], v[86:87], s[8:9], v[198:199] op_sel_hi:[1,0,0] neg_lo:[0,0,1] neg_hi:[0,0,1]
	v_exp_f32_e32 v216, v2
	v_exp_f32_e32 v217, v3
	v_pk_fma_f32 v[2:3], v[84:85], s[8:9], v[198:199] op_sel_hi:[1,0,0] neg_lo:[0,0,1] neg_hi:[0,0,1]
	v_exp_f32_e32 v220, v6
	v_exp_f32_e32 v218, v2
	v_exp_f32_e32 v219, v3
	ds_read_b128 v[2:5], v0 offset:25600
	ds_read_b128 v[10:13], v0 offset:25632
	v_exp_f32_e32 v221, v7
	v_cvt_pk_bf16_f32 v6, v14, v15
	v_cvt_pk_bf16_f32 v7, v216, v217
	v_cvt_pk_bf16_f32 v8, v218, v219
	v_cvt_pk_bf16_f32 v9, v220, v221
	v_pk_fma_f32 v[84:85], v[88:89], s[8:9], v[198:199] op_sel_hi:[1,0,0] neg_lo:[0,0,1] neg_hi:[0,0,1]
	s_xor_b64 s[40:41], s[28:29], -1
	s_waitcnt lgkmcnt(1)
	s_setprio 1
	v_mfma_f32_32x32x16_bf16 v[64:79], v[2:5], v[6:9], v[64:79]
	s_setprio 0
	ds_read_b128 v[2:5], v0 offset:30208
	ds_read_b128 v[80:83], v0 offset:30240
	v_exp_f32_e32 v88, v84
	v_exp_f32_e32 v89, v85
	s_mov_b32 s38, 1
	s_mov_b64 s[28:29], 0
	s_and_b64 vcc, exec, s[40:41]
	s_waitcnt lgkmcnt(1)
	s_setprio 1
	v_mfma_f32_32x32x16_bf16 v[48:63], v[2:5], v[6:9], v[48:63]
	ds_read_b128 v[2:5], v0 offset:34816
	ds_read_b128 v[84:87], v0 offset:39424
	ds_read_b128 v[212:215], v0 offset:34848
	s_waitcnt lgkmcnt(2)
	v_mfma_f32_32x32x16_bf16 v[32:47], v[2:5], v[6:9], v[32:47]
	s_setprio 0
	v_fma_f32 v2, v90, s8, -v198
	v_fma_f32 v3, v91, s8, -v198
	v_exp_f32_e32 v90, v2
	v_exp_f32_e32 v91, v3
	v_pk_fma_f32 v[2:3], v[92:93], s[8:9], v[198:199] op_sel_hi:[1,0,0] neg_lo:[0,0,1] neg_hi:[0,0,1]
	s_nop 0
	v_exp_f32_e32 v92, v2
	v_exp_f32_e32 v93, v3
	ds_read_b128 v[2:5], v0 offset:39456
	s_waitcnt lgkmcnt(2)
	s_setprio 1
	v_mfma_f32_32x32x16_bf16 v[16:31], v[84:87], v[6:9], v[16:31]
	s_setprio 0
	v_fma_f32 v6, v94, s8, -v198
	v_fma_f32 v7, v95, s8, -v198
	v_cvt_pk_bf16_f32 v8, v92, v93
	v_exp_f32_e32 v84, v6
	v_exp_f32_e32 v85, v7
	v_cvt_pk_bf16_f32 v6, v88, v89
	v_cvt_pk_bf16_f32 v7, v90, v91
	v_cvt_pk_bf16_f32 v9, v84, v85
	s_nop 1
	s_setprio 1
	v_mfma_f32_32x32x16_bf16 v[64:79], v[10:13], v[6:9], v[64:79]
	s_setprio 0
	v_add_f32_e64 v10, v216, v14
	v_add_f32_e64 v11, v217, v15
	v_add_f32_e64 v10, v218, v10
	v_add_f32_e64 v11, v219, v11
	v_pk_add_f32 v[10:11], v[220:221], v[10:11]
	s_setprio 1
	v_mfma_f32_32x32x16_bf16 v[48:63], v[80:83], v[6:9], v[48:63]
	s_setprio 0
	v_add_f32_e64 v10, v88, v10
	v_add_f32_e64 v11, v89, v11
	v_add_f32_e64 v10, v90, v10
	v_add_f32_e64 v11, v91, v11
	v_add_f32_e64 v10, v92, v10
	v_add_f32_e64 v11, v93, v11
	v_pk_add_f32 v[10:11], v[84:85], v[10:11]
	s_waitcnt lgkmcnt(1)
	s_setprio 1
	v_mfma_f32_32x32x16_bf16 v[32:47], v[212:215], v[6:9], v[32:47]
	v_add_f32_e32 v0, v10, v11
	v_add_f32_e32 v193, v193, v0
	s_waitcnt lgkmcnt(0)
	v_mfma_f32_32x32x16_bf16 v[16:31], v[2:5], v[6:9], v[16:31]
	s_setprio 0
	s_cbranch_vccnz .LBB0_680
.LBB0_685:
	v_lshl_or_b32 v0, s38, 5, v202
	v_mad_u32_u24 v0, v0, s30, v208
	ds_read_b128 v[2:5], v0
	ds_read_b128 v[6:9], v0 offset:32
	ds_read_b128 v[222:225], v0 offset:64
	ds_read_b128 v[226:229], v0 offset:96
	ds_read_b128 v[230:233], v0 offset:128
	ds_read_b128 v[234:237], v0 offset:160
	s_waitcnt lgkmcnt(5)
	s_setprio 1
	v_mfma_f32_32x32x16_bf16 v[80:95], v[2:5], v[148:151], 0
	ds_read_b128 v[2:5], v0 offset:192
	s_waitcnt lgkmcnt(5)
	v_mfma_f32_32x32x16_bf16 v[80:95], v[6:9], v[96:99], v[80:95]
	ds_read_b128 v[6:9], v0 offset:224
	s_waitcnt lgkmcnt(5)
	v_mfma_f32_32x32x16_bf16 v[80:95], v[222:225], v[100:103], v[80:95]
	ds_read_b128 v[222:225], v0 offset:256
	s_waitcnt lgkmcnt(5)
	v_mfma_f32_32x32x16_bf16 v[80:95], v[226:229], v[104:107], v[80:95]
	ds_read_b128 v[226:229], v0 offset:288
	s_waitcnt lgkmcnt(5)
	v_mfma_f32_32x32x16_bf16 v[80:95], v[230:233], v[108:111], v[80:95]
	ds_read_b128 v[230:233], v0 offset:320
	s_waitcnt lgkmcnt(5)
	v_mfma_f32_32x32x16_bf16 v[80:95], v[234:237], v[112:115], v[80:95]
	ds_read_b128 v[234:237], v0 offset:352
	s_waitcnt lgkmcnt(5)
	v_mfma_f32_32x32x16_bf16 v[80:95], v[2:5], v[116:119], v[80:95]
	s_waitcnt lgkmcnt(4)
	v_mfma_f32_32x32x16_bf16 v[80:95], v[6:9], v[120:123], v[80:95]
	s_waitcnt lgkmcnt(3)
	v_mfma_f32_32x32x16_bf16 v[80:95], v[222:225], v[124:127], v[80:95]
	s_waitcnt lgkmcnt(2)
	v_mfma_f32_32x32x16_bf16 v[80:95], v[226:229], v[128:131], v[80:95]
	s_waitcnt lgkmcnt(1)
	v_mfma_f32_32x32x16_bf16 v[80:95], v[230:233], v[132:135], v[80:95]
	s_waitcnt lgkmcnt(0)
	v_mfma_f32_32x32x16_bf16 v[80:95], v[234:237], v[140:143], v[80:95]
	s_setprio 0
	s_nop 11
	v_max_f32_e32 v0, v80, v81
	v_max3_f32 v0, v0, v82, v83
	v_max3_f32 v0, v0, v84, v85
	v_max3_f32 v0, v0, v86, v87
	v_max3_f32 v0, v0, v88, v89
	v_max3_f32 v0, v0, v90, v91
	v_max3_f32 v0, v0, v92, v93
	v_max3_f32 v0, v0, v94, v95
	v_mov_b32_e32 v2, v0
	s_nop 1
	v_permlane32_swap_b32_e32 v2, v0
	s_waitcnt lgkmcnt(0)
	v_max_f32_e32 v0, v0, v2
	v_mul_f32_e32 v0, 0x3dd53b94, v0
	v_add_f32_e32 v250, 0xc1000000, v0
	v_cmp_gt_f32_e32 vcc, v250, v198
	s_cbranch_vccz .LBB0_684
	v_max_f32_e32 v0, v0, v0
	v_max_f32_e32 v2, v198, v198
	v_max_f32_e32 v2, v2, v0
	v_sub_f32_e32 v0, v198, v2
	v_exp_f32_e32 v0, v0
	v_mov_b32_e32 v198, v2
	v_pk_mul_f32 v[78:79], v[78:79], v[0:1] op_sel_hi:[1,0]
	v_pk_mul_f32 v[76:77], v[76:77], v[0:1] op_sel_hi:[1,0]
	v_pk_mul_f32 v[74:75], v[74:75], v[0:1] op_sel_hi:[1,0]
	v_pk_mul_f32 v[72:73], v[72:73], v[0:1] op_sel_hi:[1,0]
	v_pk_mul_f32 v[70:71], v[70:71], v[0:1] op_sel_hi:[1,0]
	v_pk_mul_f32 v[68:69], v[68:69], v[0:1] op_sel_hi:[1,0]
	v_pk_mul_f32 v[66:67], v[66:67], v[0:1] op_sel_hi:[1,0]
	v_pk_mul_f32 v[64:65], v[64:65], v[0:1] op_sel_hi:[1,0]
	v_pk_mul_f32 v[62:63], v[62:63], v[0:1] op_sel_hi:[1,0]
	v_pk_mul_f32 v[60:61], v[60:61], v[0:1] op_sel_hi:[1,0]
	v_pk_mul_f32 v[58:59], v[58:59], v[0:1] op_sel_hi:[1,0]
	v_pk_mul_f32 v[56:57], v[56:57], v[0:1] op_sel_hi:[1,0]
	v_pk_mul_f32 v[54:55], v[54:55], v[0:1] op_sel_hi:[1,0]
	v_pk_mul_f32 v[52:53], v[52:53], v[0:1] op_sel_hi:[1,0]
	v_pk_mul_f32 v[50:51], v[50:51], v[0:1] op_sel_hi:[1,0]
	v_pk_mul_f32 v[48:49], v[48:49], v[0:1] op_sel_hi:[1,0]
	v_pk_mul_f32 v[46:47], v[46:47], v[0:1] op_sel_hi:[1,0]
	v_pk_mul_f32 v[44:45], v[44:45], v[0:1] op_sel_hi:[1,0]
	v_pk_mul_f32 v[42:43], v[42:43], v[0:1] op_sel_hi:[1,0]
	v_pk_mul_f32 v[40:41], v[40:41], v[0:1] op_sel_hi:[1,0]
	v_pk_mul_f32 v[38:39], v[38:39], v[0:1] op_sel_hi:[1,0]
	v_pk_mul_f32 v[36:37], v[36:37], v[0:1] op_sel_hi:[1,0]
	v_pk_mul_f32 v[34:35], v[34:35], v[0:1] op_sel_hi:[1,0]
	v_pk_mul_f32 v[32:33], v[32:33], v[0:1] op_sel_hi:[1,0]
	v_pk_mul_f32 v[30:31], v[30:31], v[0:1] op_sel_hi:[1,0]
	v_pk_mul_f32 v[28:29], v[28:29], v[0:1] op_sel_hi:[1,0]
	v_pk_mul_f32 v[26:27], v[26:27], v[0:1] op_sel_hi:[1,0]
	v_pk_mul_f32 v[24:25], v[24:25], v[0:1] op_sel_hi:[1,0]
	v_pk_mul_f32 v[22:23], v[22:23], v[0:1] op_sel_hi:[1,0]
	v_pk_mul_f32 v[20:21], v[20:21], v[0:1] op_sel_hi:[1,0]
	v_pk_mul_f32 v[18:19], v[18:19], v[0:1] op_sel_hi:[1,0]
	v_pk_mul_f32 v[16:17], v[16:17], v[0:1] op_sel_hi:[1,0]
	v_mul_f32_e32 v193, v193, v0
	s_branch .LBB0_684

.LBB0_1019:
	v_mov_b32_e32 v3, v180
	v_pk_fma_f32 v[4:5], v[80:81], s[18:19], v[2:3] op_sel_hi:[1,0,1] neg_lo:[0,0,1] neg_hi:[0,0,1]
	v_pk_fma_f32 v[8:9], v[86:87], s[18:19], v[2:3] op_sel_hi:[1,0,1] neg_lo:[0,0,1] neg_hi:[0,0,1]
	v_exp_f32_e32 v196, v4
	v_exp_f32_e32 v197, v5
	v_pk_fma_f32 v[4:5], v[82:83], s[18:19], v[2:3] op_sel_hi:[1,0,1] neg_lo:[0,0,1] neg_hi:[0,0,1]
	v_exp_f32_e32 v210, v8
	v_exp_f32_e32 v206, v4
	v_exp_f32_e32 v207, v5
	v_pk_fma_f32 v[4:5], v[84:85], s[18:19], v[2:3] op_sel_hi:[1,0,1] neg_lo:[0,0,1] neg_hi:[0,0,1]
	v_exp_f32_e32 v211, v9
	v_exp_f32_e32 v208, v4
	v_exp_f32_e32 v209, v5
	ds_read_b128 v[4:7], v194 offset:9280
	ds_read_b128 v[12:15], v194 offset:9312
	v_cvt_pk_bf16_f32 v8, v196, v197
	v_cvt_pk_bf16_f32 v9, v206, v207
	v_cvt_pk_bf16_f32 v10, v208, v209
	v_cvt_pk_bf16_f32 v11, v210, v211
	v_pk_fma_f32 v[84:85], v[88:89], s[18:19], v[2:3] op_sel_hi:[1,0,1] neg_lo:[0,0,1] neg_hi:[0,0,1]
	v_lshl_add_u64 v[178:179], v[178:179], 0, s[20:21]
	s_waitcnt lgkmcnt(1)
	s_setprio 1
	v_mfma_f32_32x32x16_bf16 v[64:79], v[4:7], v[8:11], v[64:79]
	s_setprio 0
	ds_read_b128 v[4:7], v194 offset:13888
	ds_read_b128 v[80:83], v194 offset:13920
	v_exp_f32_e32 v88, v84
	v_exp_f32_e32 v89, v85
	v_lshl_add_u64 v[176:177], v[176:177], 0, s[20:21]
	v_lshl_add_u64 v[174:175], v[174:175], 0, s[20:21]
	v_lshl_add_u64 v[172:173], v[172:173], 0, s[20:21]
	s_cmp_eq_u32 s31, s0
	s_waitcnt lgkmcnt(1)
	s_setprio 1
	v_mfma_f32_32x32x16_bf16 v[48:63], v[4:7], v[8:11], v[48:63]
	ds_read_b128 v[4:7], v194 offset:18496
	ds_read_b128 v[84:87], v194 offset:23104
	ds_read_b128 v[202:205], v194 offset:18528
	v_lshl_add_u64 v[170:171], v[170:171], 0, s[22:23]
	s_waitcnt lgkmcnt(2)
	v_mfma_f32_32x32x16_bf16 v[32:47], v[4:7], v[8:11], v[32:47]
	s_setprio 0
	v_fma_f32 v4, v90, s18, -v2
	v_fma_f32 v5, v91, s18, -v3
	v_exp_f32_e32 v90, v4
	v_exp_f32_e32 v91, v5
	v_pk_fma_f32 v[4:5], v[92:93], s[18:19], v[2:3] op_sel_hi:[1,0,1] neg_lo:[0,0,1] neg_hi:[0,0,1]
	v_pk_fma_f32 v[2:3], v[94:95], s[18:19], v[2:3] op_sel_hi:[1,0,1] neg_lo:[0,0,1] neg_hi:[0,0,1]
	v_exp_f32_e32 v92, v4
	v_exp_f32_e32 v93, v5
	ds_read_b128 v[4:7], v194 offset:23136
	s_waitcnt lgkmcnt(2)
	s_setprio 1
	v_mfma_f32_32x32x16_bf16 v[16:31], v[84:87], v[8:11], v[16:31]
	s_setprio 0
	v_exp_f32_e32 v2, v2
	v_exp_f32_e32 v3, v3
	v_cvt_pk_bf16_f32 v8, v88, v89
	v_cvt_pk_bf16_f32 v9, v90, v91
	v_cvt_pk_bf16_f32 v10, v92, v93
	v_cvt_pk_bf16_f32 v11, v2, v3
	s_nop 1
	s_setprio 1
	v_mfma_f32_32x32x16_bf16 v[64:79], v[12:15], v[8:11], v[64:79]
	s_setprio 0
	v_add_f32_e64 v12, v206, v196
	v_add_f32_e64 v13, v207, v197
	v_add_f32_e64 v12, v208, v12
	v_add_f32_e64 v13, v209, v13
	v_pk_add_f32 v[12:13], v[210:211], v[12:13]
	s_setprio 1
	v_mfma_f32_32x32x16_bf16 v[48:63], v[80:83], v[8:11], v[48:63]
	s_setprio 0
	v_add_f32_e64 v12, v88, v12
	v_add_f32_e64 v13, v89, v13
	v_add_f32_e64 v12, v90, v12
	v_add_f32_e64 v13, v91, v13
	v_add_f32_e64 v12, v92, v12
	v_add_f32_e64 v13, v93, v13
	v_pk_add_f32 v[2:3], v[2:3], v[12:13]
	s_waitcnt lgkmcnt(1)
	s_setprio 1
	v_mfma_f32_32x32x16_bf16 v[32:47], v[202:205], v[8:11], v[32:47]
	v_add_f32_e32 v2, v2, v3
	v_add_f32_e32 v196, v1, v2
	s_waitcnt lgkmcnt(0)
	v_mfma_f32_32x32x16_bf16 v[16:31], v[4:7], v[8:11], v[16:31]
	s_setprio 0
	s_cbranch_scc1 .LBB0_1026

.LBB0_1022:
	ds_read_b128 v[2:5], v193
	ds_read_b128 v[6:9], v193 offset:32
	s_waitcnt lgkmcnt(1)
	s_setprio 1
	v_mfma_f32_32x32x16_bf16 v[80:95], v[2:5], v[96:99], 0
	s_waitcnt lgkmcnt(0)
	v_mfma_f32_32x32x16_bf16 v[80:95], v[6:9], v[100:103], v[80:95]
	ds_read_b128 v[2:5], v193 offset:64
	ds_read_b128 v[6:9], v193 offset:96
	s_waitcnt lgkmcnt(1)
	v_mfma_f32_32x32x16_bf16 v[80:95], v[2:5], v[104:107], v[80:95]
	s_waitcnt lgkmcnt(0)
	v_mfma_f32_32x32x16_bf16 v[80:95], v[6:9], v[108:111], v[80:95]
	s_setprio 0
	s_nop 11
	v_max_f32_e32 v1, v80, v81
	v_max3_f32 v1, v1, v82, v83
	v_max3_f32 v1, v1, v84, v85
	v_max3_f32 v1, v1, v86, v87
	v_max3_f32 v1, v1, v88, v89
	v_max3_f32 v1, v1, v90, v91
	v_max3_f32 v1, v1, v92, v93
	v_max3_f32 v1, v1, v94, v95
	v_mov_b32_e32 v2, v1
	s_nop 1
	v_permlane32_swap_b32_e32 v2, v1
	s_waitcnt lgkmcnt(0)
	v_max_f32_e32 v1, v1, v2
	v_mul_f32_e32 v1, 0x3e38aa3b, v1
	v_add_f32_e32 v250, 0xc1000000, v1
	v_cmp_gt_f32_e32 vcc, v250, v180
	s_cbranch_vccz .LBB0_1024
	v_max_f32_e32 v1, v1, v1
	v_max_f32_e32 v2, v180, v180
	v_max_f32_e32 v1, v2, v1
	v_sub_f32_e32 v2, v180, v1
	v_exp_f32_e32 v2, v2
	v_mov_b32_e32 v180, v1
	v_pk_mul_f32 v[78:79], v[78:79], v[2:3] op_sel_hi:[1,0]
	v_pk_mul_f32 v[76:77], v[76:77], v[2:3] op_sel_hi:[1,0]
	v_pk_mul_f32 v[74:75], v[74:75], v[2:3] op_sel_hi:[1,0]
	v_pk_mul_f32 v[72:73], v[72:73], v[2:3] op_sel_hi:[1,0]
	v_pk_mul_f32 v[70:71], v[70:71], v[2:3] op_sel_hi:[1,0]
	v_pk_mul_f32 v[68:69], v[68:69], v[2:3] op_sel_hi:[1,0]
	v_pk_mul_f32 v[66:67], v[66:67], v[2:3] op_sel_hi:[1,0]
	v_pk_mul_f32 v[64:65], v[64:65], v[2:3] op_sel_hi:[1,0]
	v_pk_mul_f32 v[62:63], v[62:63], v[2:3] op_sel_hi:[1,0]
	v_pk_mul_f32 v[60:61], v[60:61], v[2:3] op_sel_hi:[1,0]
	v_pk_mul_f32 v[58:59], v[58:59], v[2:3] op_sel_hi:[1,0]
	v_pk_mul_f32 v[56:57], v[56:57], v[2:3] op_sel_hi:[1,0]
	v_pk_mul_f32 v[54:55], v[54:55], v[2:3] op_sel_hi:[1,0]
	v_pk_mul_f32 v[52:53], v[52:53], v[2:3] op_sel_hi:[1,0]
	v_pk_mul_f32 v[50:51], v[50:51], v[2:3] op_sel_hi:[1,0]
	v_pk_mul_f32 v[48:49], v[48:49], v[2:3] op_sel_hi:[1,0]
	v_pk_mul_f32 v[46:47], v[46:47], v[2:3] op_sel_hi:[1,0]
	v_pk_mul_f32 v[44:45], v[44:45], v[2:3] op_sel_hi:[1,0]
	v_pk_mul_f32 v[42:43], v[42:43], v[2:3] op_sel_hi:[1,0]
	v_pk_mul_f32 v[40:41], v[40:41], v[2:3] op_sel_hi:[1,0]
	v_pk_mul_f32 v[38:39], v[38:39], v[2:3] op_sel_hi:[1,0]
	v_pk_mul_f32 v[36:37], v[36:37], v[2:3] op_sel_hi:[1,0]
	v_pk_mul_f32 v[34:35], v[34:35], v[2:3] op_sel_hi:[1,0]
	v_pk_mul_f32 v[32:33], v[32:33], v[2:3] op_sel_hi:[1,0]
	v_pk_mul_f32 v[30:31], v[30:31], v[2:3] op_sel_hi:[1,0]
	v_pk_mul_f32 v[28:29], v[28:29], v[2:3] op_sel_hi:[1,0]
	v_pk_mul_f32 v[26:27], v[26:27], v[2:3] op_sel_hi:[1,0]
	v_pk_mul_f32 v[24:25], v[24:25], v[2:3] op_sel_hi:[1,0]
	v_pk_mul_f32 v[22:23], v[22:23], v[2:3] op_sel_hi:[1,0]
	v_pk_mul_f32 v[20:21], v[20:21], v[2:3] op_sel_hi:[1,0]
	v_pk_mul_f32 v[18:19], v[18:19], v[2:3] op_sel_hi:[1,0]
	v_pk_mul_f32 v[16:17], v[16:17], v[2:3] op_sel_hi:[1,0]
	v_mul_f32_e32 v196, v196, v2
.LBB0_1024:
	v_pk_fma_f32 v[2:3], v[80:81], s[18:19], v[180:181] op_sel_hi:[1,0,0] neg_lo:[0,0,1] neg_hi:[0,0,1]
	v_pk_fma_f32 v[6:7], v[86:87], s[18:19], v[180:181] op_sel_hi:[1,0,0] neg_lo:[0,0,1] neg_hi:[0,0,1]
	v_exp_f32_e32 v214, v2
	v_exp_f32_e32 v215, v3
	v_pk_fma_f32 v[2:3], v[82:83], s[18:19], v[180:181] op_sel_hi:[1,0,0] neg_lo:[0,0,1] neg_hi:[0,0,1]
	v_exp_f32_e32 v220, v6
	v_exp_f32_e32 v216, v2
	v_exp_f32_e32 v217, v3
	v_pk_fma_f32 v[2:3], v[84:85], s[18:19], v[180:181] op_sel_hi:[1,0,0] neg_lo:[0,0,1] neg_hi:[0,0,1]
	v_exp_f32_e32 v221, v7
	v_exp_f32_e32 v218, v2
	v_exp_f32_e32 v219, v3
	ds_read_b128 v[2:5], v194 offset:9216
	ds_read_b128 v[10:13], v194 offset:9248
	v_cvt_pk_bf16_f32 v6, v214, v215
	v_cvt_pk_bf16_f32 v7, v216, v217
	v_cvt_pk_bf16_f32 v8, v218, v219
	v_cvt_pk_bf16_f32 v9, v220, v221
	v_pk_fma_f32 v[14:15], v[88:89], s[18:19], v[180:181] op_sel_hi:[1,0,0] neg_lo:[0,0,1] neg_hi:[0,0,1]
	s_waitcnt lgkmcnt(1)
	s_setprio 1
	v_mfma_f32_32x32x16_bf16 v[64:79], v[2:5], v[6:9], v[64:79]
	ds_read_b128 v[2:5], v194 offset:13824
	ds_read_b128 v[202:205], v194 offset:13856
	v_exp_f32_e32 v222, v14
	v_exp_f32_e32 v223, v15
	s_waitcnt lgkmcnt(1)
	v_mfma_f32_32x32x16_bf16 v[48:63], v[2:5], v[6:9], v[48:63]
	ds_read_b128 v[2:5], v194 offset:18432
	ds_read_b128 v[80:83], v194 offset:23040
	ds_read_b128 v[206:209], v194 offset:18464
	ds_read_b128 v[210:213], v194 offset:23072
	s_waitcnt lgkmcnt(3)
	v_mfma_f32_32x32x16_bf16 v[32:47], v[2:5], v[6:9], v[32:47]
	s_setprio 0
	v_fma_f32 v4, v92, s18, -v180
	v_fma_f32 v5, v93, s18, -v180
	v_fma_f32 v2, v90, s18, -v180
	v_fma_f32 v3, v91, s18, -v180
	v_exp_f32_e32 v224, v4
	v_exp_f32_e32 v225, v5
	v_pk_fma_f32 v[4:5], v[94:95], s[18:19], v[180:181] op_sel_hi:[1,0,0] neg_lo:[0,0,1] neg_hi:[0,0,1]
	v_exp_f32_e32 v2, v2
	v_exp_f32_e32 v3, v3
	v_exp_f32_e32 v226, v4
	v_exp_f32_e32 v227, v5
	s_waitcnt lgkmcnt(2)
	s_setprio 1
	v_mfma_f32_32x32x16_bf16 v[16:31], v[80:83], v[6:9], v[16:31]
	v_cvt_pk_bf16_f32 v4, v222, v223
	v_cvt_pk_bf16_f32 v5, v2, v3
	v_cvt_pk_bf16_f32 v6, v224, v225
	v_cvt_pk_bf16_f32 v7, v226, v227
	s_nop 1
	v_mfma_f32_32x32x16_bf16 v[64:79], v[10:13], v[4:7], v[64:79]
	ds_read_b128 v[8:11], v193 offset:4608
	ds_read_b128 v[12:15], v193 offset:4640
	s_waitcnt lgkmcnt(1)
	v_mfma_f32_32x32x16_bf16 v[80:95], v[8:11], v[96:99], 0
	s_waitcnt lgkmcnt(0)
	v_mfma_f32_32x32x16_bf16 v[80:95], v[12:15], v[100:103], v[80:95]
	ds_read_b128 v[8:11], v193 offset:4672
	ds_read_b128 v[12:15], v193 offset:4704
	s_waitcnt lgkmcnt(1)
	v_mfma_f32_32x32x16_bf16 v[80:95], v[8:11], v[104:107], v[80:95]
	s_setprio 0
	v_add_f32_e64 v8, v216, v214
	v_add_f32_e64 v9, v217, v215
	v_add_f32_e64 v8, v218, v8
	v_add_f32_e64 v9, v219, v9
	v_pk_add_f32 v[8:9], v[220:221], v[8:9]
	s_waitcnt lgkmcnt(0)
	s_setprio 1
	v_mfma_f32_32x32x16_bf16 v[80:95], v[12:15], v[108:111], v[80:95]
	s_setprio 0
	v_add_f32_e64 v8, v222, v8
	v_add_f32_e64 v9, v223, v9
	v_add_f32_e64 v2, v2, v8
	v_add_f32_e64 v3, v3, v9
	v_add_f32_e64 v2, v224, v2
	v_add_f32_e64 v3, v225, v3
	s_nop 5
	v_max_f32_e32 v1, v80, v81
	v_max3_f32 v1, v1, v82, v83
	v_max3_f32 v1, v1, v84, v85
	v_max3_f32 v1, v1, v86, v87
	v_max3_f32 v1, v1, v88, v89
	v_max3_f32 v1, v1, v90, v91
	v_max3_f32 v1, v1, v92, v93
	v_max3_f32 v8, v1, v94, v95
	ds_bpermute_b32 v9, v184, v8
	s_setprio 1
	v_mfma_f32_32x32x16_bf16 v[48:63], v[202:205], v[4:7], v[48:63]
	s_setprio 0
	v_add_f32_e64 v2, v226, v2
	v_add_f32_e64 v3, v227, v3
	v_add_f32_e32 v1, v2, v3
	s_waitcnt lgkmcnt(0)
	v_max_f32_e32 v2, v9, v9
	v_max_f32_e32 v2, v8, v2
	v_mul_f32_e32 v2, 0x3e38aa3b, v2
	v_add_f32_e32 v1, v196, v1
	s_setprio 1
	v_mfma_f32_32x32x16_bf16 v[32:47], v[206:209], v[4:7], v[32:47]
	v_add_f32_e32 v250, 0xc1000000, v2
	v_cmp_gt_f32_e32 vcc, v250, v180
	v_mfma_f32_32x32x16_bf16 v[16:31], v[210:213], v[4:7], v[16:31]
	s_setprio 0
	s_cbranch_vccnz .LBB0_1018
	v_mov_b64_e32 v[2:3], v[180:181]
	s_branch .LBB0_1019

.LBB0_1285:
	v_pk_fma_f32 v[64:65], v[64:65], s[18:19], v[152:153] op_sel_hi:[1,0,1] neg_lo:[0,0,1] neg_hi:[0,0,1]
	v_pk_fma_f32 v[72:73], v[72:73], s[18:19], v[152:153] op_sel_hi:[1,0,1] neg_lo:[0,0,1] neg_hi:[0,0,1]
	v_exp_f32_e32 v98, v64
	v_exp_f32_e32 v99, v65
	v_pk_fma_f32 v[64:65], v[66:67], s[18:19], v[152:153] op_sel_hi:[1,0,1] neg_lo:[0,0,1] neg_hi:[0,0,1]
	ds_read_b128 v[82:85], v171 offset:17504
	v_exp_f32_e32 v100, v64
	v_exp_f32_e32 v101, v65
	v_pk_fma_f32 v[64:65], v[68:69], s[18:19], v[152:153] op_sel_hi:[1,0,1] neg_lo:[0,0,1] neg_hi:[0,0,1]
	v_pk_fma_f32 v[68:69], v[70:71], s[18:19], v[152:153] op_sel_hi:[1,0,1] neg_lo:[0,0,1] neg_hi:[0,0,1]
	v_exp_f32_e32 v102, v64
	v_exp_f32_e32 v103, v65
	ds_read_b128 v[64:67], v171 offset:17472
	v_exp_f32_e32 v104, v68
	v_exp_f32_e32 v105, v69
	v_cvt_pk_bf16_f32 v68, v98, v99
	v_cvt_pk_bf16_f32 v69, v100, v101
	v_cvt_pk_bf16_f32 v70, v102, v103
	v_cvt_pk_bf16_f32 v71, v104, v105
	v_exp_f32_e32 v72, v72
	v_exp_f32_e32 v73, v73
	s_waitcnt lgkmcnt(0)
	s_setprio 1
	v_mfma_f32_32x32x16_bf16 v[48:63], v[64:67], v[68:71], v[48:63]
	s_setprio 0
	ds_read_b128 v[64:67], v171 offset:22080
	ds_read_b128 v[86:89], v171 offset:22112
	s_lshl_b32 s8, s24, 1
	s_add_i32 s41, s41, s33
	s_cmpk_gt_i32 s41, 0x3ff
	s_waitcnt lgkmcnt(1)
	s_setprio 1
	v_mfma_f32_32x32x16_bf16 v[32:47], v[64:67], v[68:71], v[32:47]
	ds_read_b128 v[64:67], v171 offset:26688
	ds_read_b128 v[90:93], v171 offset:31296
	ds_read_b128 v[94:97], v171 offset:26720
	s_waitcnt lgkmcnt(2)
	v_mfma_f32_32x32x16_bf16 v[16:31], v[64:67], v[68:71], v[16:31]
	s_setprio 0
	v_fma_f32 v64, v74, s18, -v152
	v_fma_f32 v65, v75, s18, -v153
	v_exp_f32_e32 v74, v64
	v_exp_f32_e32 v75, v65
	v_pk_fma_f32 v[64:65], v[76:77], s[18:19], v[152:153] op_sel_hi:[1,0,1] neg_lo:[0,0,1] neg_hi:[0,0,1]
	s_nop 0
	v_exp_f32_e32 v76, v64
	s_waitcnt lgkmcnt(1)
	s_setprio 1
	v_mfma_f32_32x32x16_bf16 v[0:15], v[90:93], v[68:71], v[0:15]
	s_setprio 0
	v_fma_f32 v68, v78, s18, -v152
	v_fma_f32 v69, v79, s18, -v153
	v_exp_f32_e32 v77, v65
	v_exp_f32_e32 v78, v68
	v_exp_f32_e32 v79, v69
	v_cvt_pk_bf16_f32 v68, v72, v73
	v_cvt_pk_bf16_f32 v69, v74, v75
	v_cvt_pk_bf16_f32 v70, v76, v77
	v_cvt_pk_bf16_f32 v71, v78, v79
	ds_read_b128 v[64:67], v171 offset:31328
	s_nop 0
	s_setprio 1
	v_mfma_f32_32x32x16_bf16 v[48:63], v[82:85], v[68:71], v[48:63]
	s_setprio 0
	v_add_f32_e64 v82, v100, v98
	v_add_f32_e64 v83, v101, v99
	v_add_f32_e64 v82, v102, v82
	v_add_f32_e64 v83, v103, v83
	v_pk_add_f32 v[82:83], v[104:105], v[82:83]
	s_setprio 1
	v_mfma_f32_32x32x16_bf16 v[32:47], v[86:89], v[68:71], v[32:47]
	s_setprio 0
	v_add_f32_e64 v72, v72, v82
	v_add_f32_e64 v73, v73, v83
	v_add_f32_e64 v72, v74, v72
	v_add_f32_e64 v73, v75, v73
	v_add_f32_e64 v72, v76, v72
	v_add_f32_e64 v73, v77, v73
	v_pk_add_f32 v[72:73], v[78:79], v[72:73]
	s_waitcnt lgkmcnt(1)
	s_setprio 1
	v_mfma_f32_32x32x16_bf16 v[16:31], v[94:97], v[68:71], v[16:31]
	s_setprio 0
	v_add_f32_e32 v72, v72, v73
	v_add_f32_e32 v74, v80, v72
	ds_bpermute_b32 v75, v168, v74
	v_lshl_add_u64 v[72:73], s[6:7], 0, v[150:151]
	v_lshl_add_u64 v[72:73], v[72:73], 0, s[8:9]
	s_waitcnt lgkmcnt(0)
	v_add_f32_e32 v74, v74, v75
	v_div_scale_f32 v75, s[26:27], v74, v74, 1.0
	v_rcp_f32_e32 v76, v75
	s_setprio 1
	v_mfma_f32_32x32x16_bf16 v[0:15], v[64:67], v[68:71], v[0:15]
	s_setprio 0
	v_fma_f32 v64, -v75, v76, 1.0
	v_fmac_f32_e32 v76, v64, v76
	v_div_scale_f32 v64, vcc, 1.0, v74, 1.0
	v_mul_f32_e32 v65, v64, v76
	v_fma_f32 v66, -v75, v65, v64
	v_fmac_f32_e32 v65, v66, v76
	v_fma_f32 v64, -v75, v65, v64
	v_div_fmas_f32 v64, v64, v76, v65
	v_div_fixup_f32 v64, v64, v74, 1.0
	v_pk_mul_f32 v[48:49], v[48:49], v[64:65] op_sel_hi:[1,0]
	v_pk_mul_f32 v[50:51], v[50:51], v[64:65] op_sel_hi:[1,0]
	v_pk_mul_f32 v[32:33], v[32:33], v[64:65] op_sel_hi:[1,0]
	v_pk_mul_f32 v[34:35], v[34:35], v[64:65] op_sel_hi:[1,0]
	v_pk_mul_f32 v[16:17], v[16:17], v[64:65] op_sel_hi:[1,0]
	v_pk_mul_f32 v[18:19], v[18:19], v[64:65] op_sel_hi:[1,0]
	v_pk_mul_f32 v[0:1], v[0:1], v[64:65] op_sel_hi:[1,0]
	v_pk_mul_f32 v[2:3], v[2:3], v[64:65] op_sel_hi:[1,0]
	v_pk_mul_f32 v[52:53], v[52:53], v[64:65] op_sel_hi:[1,0]
	v_pk_mul_f32 v[54:55], v[54:55], v[64:65] op_sel_hi:[1,0]
	v_pk_mul_f32 v[56:57], v[56:57], v[64:65] op_sel_hi:[1,0]
	v_pk_mul_f32 v[58:59], v[58:59], v[64:65] op_sel_hi:[1,0]
	v_pk_mul_f32 v[60:61], v[60:61], v[64:65] op_sel_hi:[1,0]
	v_pk_mul_f32 v[62:63], v[62:63], v[64:65] op_sel_hi:[1,0]
	v_pk_mul_f32 v[36:37], v[36:37], v[64:65] op_sel_hi:[1,0]
	v_pk_mul_f32 v[38:39], v[38:39], v[64:65] op_sel_hi:[1,0]
	v_pk_mul_f32 v[40:41], v[40:41], v[64:65] op_sel_hi:[1,0]
	v_pk_mul_f32 v[42:43], v[42:43], v[64:65] op_sel_hi:[1,0]
	v_pk_mul_f32 v[44:45], v[44:45], v[64:65] op_sel_hi:[1,0]
	v_pk_mul_f32 v[46:47], v[46:47], v[64:65] op_sel_hi:[1,0]
	v_pk_mul_f32 v[20:21], v[20:21], v[64:65] op_sel_hi:[1,0]
	v_pk_mul_f32 v[22:23], v[22:23], v[64:65] op_sel_hi:[1,0]
	v_pk_mul_f32 v[24:25], v[24:25], v[64:65] op_sel_hi:[1,0]
	v_pk_mul_f32 v[26:27], v[26:27], v[64:65] op_sel_hi:[1,0]
	v_pk_mul_f32 v[28:29], v[28:29], v[64:65] op_sel_hi:[1,0]
	v_pk_mul_f32 v[30:31], v[30:31], v[64:65] op_sel_hi:[1,0]
	v_pk_mul_f32 v[4:5], v[4:5], v[64:65] op_sel_hi:[1,0]
	v_pk_mul_f32 v[6:7], v[6:7], v[64:65] op_sel_hi:[1,0]
	v_pk_mul_f32 v[8:9], v[8:9], v[64:65] op_sel_hi:[1,0]
	v_pk_mul_f32 v[10:11], v[10:11], v[64:65] op_sel_hi:[1,0]
	v_pk_mul_f32 v[12:13], v[12:13], v[64:65] op_sel_hi:[1,0]
	v_pk_mul_f32 v[14:15], v[14:15], v[64:65] op_sel_hi:[1,0]
	v_lshl_add_u64 v[64:65], v[72:73], 0, v[144:145]
	v_cvt_pk_bf16_f32 v48, v48, v49
	v_cvt_pk_bf16_f32 v49, v50, v51
	v_cvt_pk_bf16_f32 v32, v32, v33
	v_cvt_pk_bf16_f32 v33, v34, v35
	v_cvt_pk_bf16_f32 v16, v16, v17
	v_cvt_pk_bf16_f32 v17, v18, v19
	v_cvt_pk_bf16_f32 v0, v0, v1
	v_cvt_pk_bf16_f32 v1, v2, v3
	global_store_dwordx2 v[64:65], v[48:49], off sc1
	v_cvt_pk_bf16_f32 v48, v52, v53
	v_cvt_pk_bf16_f32 v49, v54, v55
	global_store_dwordx2 v[64:65], v[32:33], off offset:64 sc1
	v_cvt_pk_bf16_f32 v32, v36, v37
	v_cvt_pk_bf16_f32 v33, v38, v39
	global_store_dwordx2 v[64:65], v[16:17], off offset:128 sc1
	v_cvt_pk_bf16_f32 v16, v20, v21
	v_cvt_pk_bf16_f32 v17, v22, v23
	global_store_dwordx2 v[64:65], v[0:1], off offset:192 sc1
	v_cvt_pk_bf16_f32 v0, v4, v5
	v_cvt_pk_bf16_f32 v1, v6, v7
	global_store_dwordx2 v[64:65], v[48:49], off offset:16 sc1
	v_cvt_pk_bf16_f32 v48, v56, v57
	v_cvt_pk_bf16_f32 v49, v58, v59
	global_store_dwordx2 v[64:65], v[32:33], off offset:80 sc1
	v_cvt_pk_bf16_f32 v32, v40, v41
	v_cvt_pk_bf16_f32 v33, v42, v43
	global_store_dwordx2 v[64:65], v[16:17], off offset:144 sc1
	v_cvt_pk_bf16_f32 v16, v24, v25
	v_cvt_pk_bf16_f32 v17, v26, v27
	global_store_dwordx2 v[64:65], v[0:1], off offset:208 sc1
	v_cvt_pk_bf16_f32 v0, v8, v9
	v_cvt_pk_bf16_f32 v1, v10, v11
	global_store_dwordx2 v[64:65], v[48:49], off offset:32 sc1
	v_cvt_pk_bf16_f32 v48, v60, v61
	v_cvt_pk_bf16_f32 v49, v62, v63
	global_store_dwordx2 v[64:65], v[32:33], off offset:96 sc1
	v_cvt_pk_bf16_f32 v32, v44, v45
	v_cvt_pk_bf16_f32 v33, v46, v47
	global_store_dwordx2 v[64:65], v[16:17], off offset:160 sc1
	v_cvt_pk_bf16_f32 v16, v28, v29
	v_cvt_pk_bf16_f32 v17, v30, v31
	global_store_dwordx2 v[64:65], v[0:1], off offset:224 sc1
	v_cvt_pk_bf16_f32 v0, v12, v13
	v_cvt_pk_bf16_f32 v1, v14, v15
	global_store_dwordx2 v[64:65], v[48:49], off offset:48 sc1
	global_store_dwordx2 v[64:65], v[32:33], off offset:112 sc1
	global_store_dwordx2 v[64:65], v[16:17], off offset:176 sc1
	global_store_dwordx2 v[64:65], v[0:1], off offset:240 sc1
	s_cbranch_scc1 .LBB0_1306

.LBB0_1296:
	v_pk_fma_f32 v[64:65], v[64:65], s[18:19], v[152:153] op_sel_hi:[1,0,1] neg_lo:[0,0,1] neg_hi:[0,0,1]
	v_pk_fma_f32 v[72:73], v[72:73], s[18:19], v[152:153] op_sel_hi:[1,0,1] neg_lo:[0,0,1] neg_hi:[0,0,1]
	v_exp_f32_e32 v190, v64
	v_exp_f32_e32 v191, v65
	v_pk_fma_f32 v[64:65], v[66:67], s[18:19], v[152:153] op_sel_hi:[1,0,1] neg_lo:[0,0,1] neg_hi:[0,0,1]
	ds_read_b128 v[174:177], v171 offset:17504
	v_exp_f32_e32 v192, v64
	v_exp_f32_e32 v193, v65
	v_pk_fma_f32 v[64:65], v[68:69], s[18:19], v[152:153] op_sel_hi:[1,0,1] neg_lo:[0,0,1] neg_hi:[0,0,1]
	v_pk_fma_f32 v[68:69], v[70:71], s[18:19], v[152:153] op_sel_hi:[1,0,1] neg_lo:[0,0,1] neg_hi:[0,0,1]
	v_exp_f32_e32 v194, v64
	v_exp_f32_e32 v195, v65
	ds_read_b128 v[64:67], v171 offset:17472
	v_exp_f32_e32 v196, v68
	v_exp_f32_e32 v197, v69
	v_cvt_pk_bf16_f32 v68, v190, v191
	v_cvt_pk_bf16_f32 v69, v192, v193
	v_cvt_pk_bf16_f32 v70, v194, v195
	v_cvt_pk_bf16_f32 v71, v196, v197
	v_exp_f32_e32 v72, v72
	v_exp_f32_e32 v73, v73
	s_waitcnt lgkmcnt(0)
	s_setprio 1
	v_mfma_f32_32x32x16_bf16 v[48:63], v[64:67], v[68:71], v[48:63]
	s_setprio 0
	ds_read_b128 v[64:67], v171 offset:22080
	ds_read_b128 v[178:181], v171 offset:22112
	s_add_i32 s25, s25, -1
	v_lshl_add_u64 v[154:155], v[154:155], 0, s[20:21]
	v_lshl_add_u64 v[156:157], v[156:157], 0, s[20:21]
	v_lshl_add_u64 v[158:159], v[158:159], 0, s[20:21]
	v_lshl_add_u64 v[160:161], v[160:161], 0, s[20:21]
	s_cmp_eq_u32 s25, 0
	s_waitcnt lgkmcnt(1)
	s_setprio 1
	v_mfma_f32_32x32x16_bf16 v[32:47], v[64:67], v[68:71], v[32:47]
	ds_read_b128 v[64:67], v171 offset:26688
	ds_read_b128 v[182:185], v171 offset:31296
	ds_read_b128 v[186:189], v171 offset:26720
	v_lshl_add_u64 v[162:163], v[162:163], 0, s[22:23]
	s_waitcnt lgkmcnt(2)
	v_mfma_f32_32x32x16_bf16 v[16:31], v[64:67], v[68:71], v[16:31]
	s_setprio 0
	v_fma_f32 v64, v74, s18, -v152
	v_fma_f32 v65, v75, s18, -v153
	v_exp_f32_e32 v74, v64
	v_exp_f32_e32 v75, v65
	v_pk_fma_f32 v[64:65], v[76:77], s[18:19], v[152:153] op_sel_hi:[1,0,1] neg_lo:[0,0,1] neg_hi:[0,0,1]
	s_nop 0
	v_exp_f32_e32 v76, v64
	v_exp_f32_e32 v77, v65
	ds_read_b128 v[64:67], v171 offset:31328
	s_waitcnt lgkmcnt(2)
	s_setprio 1
	v_mfma_f32_32x32x16_bf16 v[0:15], v[182:185], v[68:71], v[0:15]
	s_setprio 0
	v_fma_f32 v68, v78, s18, -v152
	v_fma_f32 v69, v79, s18, -v153
	v_cvt_pk_bf16_f32 v70, v76, v77
	v_exp_f32_e32 v78, v68
	v_exp_f32_e32 v79, v69
	v_cvt_pk_bf16_f32 v68, v72, v73
	v_cvt_pk_bf16_f32 v69, v74, v75
	v_cvt_pk_bf16_f32 v71, v78, v79
	s_nop 1
	s_setprio 1
	v_mfma_f32_32x32x16_bf16 v[48:63], v[174:177], v[68:71], v[48:63]
	s_setprio 0
	v_add_f32_e64 v174, v192, v190
	v_add_f32_e64 v175, v193, v191
	v_add_f32_e64 v174, v194, v174
	v_add_f32_e64 v175, v195, v175
	v_pk_add_f32 v[174:175], v[196:197], v[174:175]
	s_setprio 1
	v_mfma_f32_32x32x16_bf16 v[32:47], v[178:181], v[68:71], v[32:47]
	s_setprio 0
	v_add_f32_e64 v72, v72, v174
	v_add_f32_e64 v73, v73, v175
	v_add_f32_e64 v72, v74, v72
	v_add_f32_e64 v73, v75, v73
	v_add_f32_e64 v72, v76, v72
	v_add_f32_e64 v73, v77, v73
	v_pk_add_f32 v[72:73], v[78:79], v[72:73]
	s_waitcnt lgkmcnt(1)
	s_setprio 1
	v_mfma_f32_32x32x16_bf16 v[16:31], v[186:189], v[68:71], v[16:31]
	v_add_f32_e32 v72, v72, v73
	v_add_f32_e32 v172, v172, v72
	s_waitcnt lgkmcnt(0)
	v_mfma_f32_32x32x16_bf16 v[0:15], v[64:67], v[68:71], v[0:15]
	s_setprio 0
	s_cbranch_scc1 .LBB0_1301
.LBB0_1297:
	s_barrier
	s_waitcnt vmcnt(3)
	ds_write_b128 v166, v[112:115]
	s_waitcnt vmcnt(2)
	ds_write_b128 v166, v[116:119] offset:4352
	s_waitcnt vmcnt(1)
	ds_write_b128 v166, v[120:123] offset:8704
	s_waitcnt vmcnt(0)
	ds_write_b128 v166, v[124:127] offset:13056
	s_waitcnt vmcnt(1)
	ds_write_b128 v167, v[140:143] offset:17408
	ds_write_b128 v167, v[132:135] offset:22016
	ds_write_b128 v167, v[128:131] offset:26624
	s_waitcnt vmcnt(0)
	ds_write_b128 v167, v[136:139] offset:31232
	s_waitcnt lgkmcnt(0)
	s_barrier
	ds_read_b128 v[64:67], v170
	ds_read_b128 v[112:115], v170 offset:32
	s_waitcnt lgkmcnt(1)
	s_setprio 1
	v_mfma_f32_32x32x16_bf16 v[64:79], v[64:67], v[108:111], 0
	s_setprio 0
	v_lshl_add_u64 v[124:125], s[14:15], 0, v[162:163]
	v_add_co_u32_e32 v178, vcc, s37, v124
	v_lshl_add_u64 v[126:127], s[14:15], 0, v[154:155]
	s_nop 0
	v_addc_co_u32_e32 v179, vcc, 0, v125, vcc
	v_add_co_u32_e32 v180, vcc, s38, v124
	s_waitcnt lgkmcnt(0)
	s_setprio 1
	v_mfma_f32_32x32x16_bf16 v[64:79], v[112:115], v[104:107], v[64:79]
	s_setprio 0
	ds_read_b128 v[112:115], v170 offset:64
	ds_read_b128 v[116:119], v170 offset:96
	v_lshl_add_u64 v[128:129], s[14:15], 0, v[156:157]
	v_lshl_add_u64 v[130:131], s[14:15], 0, v[158:159]
	v_lshl_add_u64 v[136:137], s[14:15], 0, v[160:161]
	v_addc_co_u32_e32 v181, vcc, 0, v125, vcc
	v_add_co_u32_e32 v182, vcc, s39, v124
	s_waitcnt lgkmcnt(1)
	s_setprio 1
	v_mfma_f32_32x32x16_bf16 v[64:79], v[112:115], v[100:103], v[64:79]
	s_setprio 0
	ds_read_b128 v[112:115], v170 offset:128
	v_addc_co_u32_e32 v183, vcc, 0, v125, vcc
	v_add_co_u32_e32 v124, vcc, s40, v124
	s_nop 1
	v_addc_co_u32_e32 v125, vcc, 0, v125, vcc
	s_waitcnt lgkmcnt(1)
	s_setprio 1
	v_mfma_f32_32x32x16_bf16 v[64:79], v[116:119], v[96:99], v[64:79]
	ds_read_b128 v[116:119], v170 offset:160
	ds_read_b128 v[120:123], v170 offset:192
	ds_read_b128 v[174:177], v170 offset:224
	s_waitcnt lgkmcnt(3)
	v_mfma_f32_32x32x16_bf16 v[64:79], v[112:115], v[92:95], v[64:79]
	s_waitcnt lgkmcnt(2)
	v_mfma_f32_32x32x16_bf16 v[64:79], v[116:119], v[88:91], v[64:79]
	s_setprio 0
	global_load_dwordx4 v[140:143], v[126:127], off
	global_load_dwordx4 v[132:135], v[128:129], off
	s_nop 0
	global_load_dwordx4 v[128:131], v[130:131], off
	s_nop 0
	global_load_dwordx4 v[136:139], v[136:137], off
	s_nop 0
	global_load_dwordx4 v[112:115], v[178:179], off
	global_load_dwordx4 v[116:119], v[180:181], off
	s_waitcnt lgkmcnt(1)
	s_setprio 1
	v_mfma_f32_32x32x16_bf16 v[64:79], v[120:123], v[84:87], v[64:79]
	global_load_dwordx4 v[120:123], v[182:183], off
	s_nop 0
	global_load_dwordx4 v[124:127], v[124:125], off
	s_waitcnt lgkmcnt(0)
	v_mfma_f32_32x32x16_bf16 v[64:79], v[174:177], v[80:83], v[64:79]
	s_setprio 0
	s_nop 11
	v_max_f32_e32 v152, v64, v65
	v_max3_f32 v152, v152, v66, v67
	v_max3_f32 v152, v152, v68, v69
	v_max3_f32 v152, v152, v70, v71
	v_max3_f32 v152, v152, v72, v73
	v_max3_f32 v152, v152, v74, v75
	v_max3_f32 v152, v152, v76, v77
	v_max3_f32 v152, v152, v78, v79
	v_mov_b32_e32 v173, v152
	s_nop 1
	v_permlane32_swap_b32_e32 v173, v152
	s_waitcnt lgkmcnt(0)
	v_max_f32_e32 v152, v152, v173
	v_mul_f32_e32 v152, 0x3e0293ee, v152
	v_add_f32_e32 v250, 0xc1000000, v152
	v_cmp_gt_f32_e32 vcc, v250, v153
	s_cbranch_vccz .LBB0_1299
	v_max_f32_e32 v152, v152, v152
	v_max_f32_e32 v173, v153, v153
	v_max_f32_e32 v173, v173, v152
	v_sub_f32_e32 v152, v153, v173
	v_exp_f32_e32 v152, v152
	s_nop 0
	v_pk_mul_f32 v[62:63], v[62:63], v[152:153] op_sel_hi:[1,0]
	v_pk_mul_f32 v[60:61], v[60:61], v[152:153] op_sel_hi:[1,0]
	v_pk_mul_f32 v[58:59], v[58:59], v[152:153] op_sel_hi:[1,0]
	v_pk_mul_f32 v[56:57], v[56:57], v[152:153] op_sel_hi:[1,0]
	v_pk_mul_f32 v[54:55], v[54:55], v[152:153] op_sel_hi:[1,0]
	v_pk_mul_f32 v[52:53], v[52:53], v[152:153] op_sel_hi:[1,0]
	v_pk_mul_f32 v[50:51], v[50:51], v[152:153] op_sel_hi:[1,0]
	v_pk_mul_f32 v[48:49], v[48:49], v[152:153] op_sel_hi:[1,0]
	v_pk_mul_f32 v[46:47], v[46:47], v[152:153] op_sel_hi:[1,0]
	v_pk_mul_f32 v[44:45], v[44:45], v[152:153] op_sel_hi:[1,0]
	v_pk_mul_f32 v[42:43], v[42:43], v[152:153] op_sel_hi:[1,0]
	v_pk_mul_f32 v[40:41], v[40:41], v[152:153] op_sel_hi:[1,0]
	v_pk_mul_f32 v[38:39], v[38:39], v[152:153] op_sel_hi:[1,0]
	v_pk_mul_f32 v[36:37], v[36:37], v[152:153] op_sel_hi:[1,0]
	v_pk_mul_f32 v[34:35], v[34:35], v[152:153] op_sel_hi:[1,0]
	v_pk_mul_f32 v[32:33], v[32:33], v[152:153] op_sel_hi:[1,0]
	v_pk_mul_f32 v[30:31], v[30:31], v[152:153] op_sel_hi:[1,0]
	v_pk_mul_f32 v[28:29], v[28:29], v[152:153] op_sel_hi:[1,0]
	v_pk_mul_f32 v[26:27], v[26:27], v[152:153] op_sel_hi:[1,0]
	v_pk_mul_f32 v[24:25], v[24:25], v[152:153] op_sel_hi:[1,0]
	v_pk_mul_f32 v[22:23], v[22:23], v[152:153] op_sel_hi:[1,0]
	v_pk_mul_f32 v[20:21], v[20:21], v[152:153] op_sel_hi:[1,0]
	v_pk_mul_f32 v[18:19], v[18:19], v[152:153] op_sel_hi:[1,0]
	v_pk_mul_f32 v[16:17], v[16:17], v[152:153] op_sel_hi:[1,0]
	v_pk_mul_f32 v[14:15], v[14:15], v[152:153] op_sel_hi:[1,0]
	v_pk_mul_f32 v[12:13], v[12:13], v[152:153] op_sel_hi:[1,0]
	v_pk_mul_f32 v[10:11], v[10:11], v[152:153] op_sel_hi:[1,0]
	v_pk_mul_f32 v[8:9], v[8:9], v[152:153] op_sel_hi:[1,0]
	v_pk_mul_f32 v[6:7], v[6:7], v[152:153] op_sel_hi:[1,0]
	v_pk_mul_f32 v[4:5], v[4:5], v[152:153] op_sel_hi:[1,0]
	v_pk_mul_f32 v[2:3], v[2:3], v[152:153] op_sel_hi:[1,0]
	v_pk_mul_f32 v[0:1], v[0:1], v[152:153] op_sel_hi:[1,0]
	v_mul_f32_e32 v172, v172, v152
	v_mov_b32_e32 v153, v173
.LBB0_1299:
	v_mov_b32_e32 v152, v153
	v_pk_fma_f32 v[64:65], v[64:65], s[18:19], v[152:153] op_sel_hi:[1,0,0] neg_lo:[0,0,1] neg_hi:[0,0,1]
	v_pk_fma_f32 v[72:73], v[72:73], s[18:19], v[152:153] op_sel_hi:[1,0,0] neg_lo:[0,0,1] neg_hi:[0,0,1]
	v_exp_f32_e32 v202, v64
	v_exp_f32_e32 v203, v65
	v_pk_fma_f32 v[64:65], v[66:67], s[18:19], v[152:153] op_sel_hi:[1,0,0] neg_lo:[0,0,1] neg_hi:[0,0,1]
	ds_read_b128 v[174:177], v171 offset:17440
	v_exp_f32_e32 v204, v64
	v_exp_f32_e32 v205, v65
	v_pk_fma_f32 v[64:65], v[68:69], s[18:19], v[152:153] op_sel_hi:[1,0,0] neg_lo:[0,0,1] neg_hi:[0,0,1]
	v_pk_fma_f32 v[68:69], v[70:71], s[18:19], v[152:153] op_sel_hi:[1,0,0] neg_lo:[0,0,1] neg_hi:[0,0,1]
	v_exp_f32_e32 v206, v64
	v_exp_f32_e32 v207, v65
	ds_read_b128 v[64:67], v171 offset:17408
	v_exp_f32_e32 v208, v68
	v_exp_f32_e32 v209, v69
	v_cvt_pk_bf16_f32 v68, v202, v203
	v_cvt_pk_bf16_f32 v69, v204, v205
	v_cvt_pk_bf16_f32 v70, v206, v207
	v_cvt_pk_bf16_f32 v71, v208, v209
	v_exp_f32_e32 v210, v72
	v_exp_f32_e32 v211, v73
	s_waitcnt lgkmcnt(0)
	s_setprio 1
	v_mfma_f32_32x32x16_bf16 v[48:63], v[64:67], v[68:71], v[48:63]
	ds_read_b128 v[64:67], v171 offset:22016
	ds_read_b128 v[178:181], v171 offset:22048
	s_waitcnt lgkmcnt(1)
	v_mfma_f32_32x32x16_bf16 v[32:47], v[64:67], v[68:71], v[32:47]
	ds_read_b128 v[64:67], v171 offset:26624
	ds_read_b128 v[182:185], v171 offset:31232
	ds_read_b128 v[186:189], v171 offset:26656
	ds_read_b128 v[190:193], v171 offset:31264
	s_waitcnt lgkmcnt(3)
	v_mfma_f32_32x32x16_bf16 v[16:31], v[64:67], v[68:71], v[16:31]
	s_setprio 0
	v_fma_f32 v64, v74, s18, -v152
	v_fma_f32 v65, v75, s18, -v152
	v_exp_f32_e32 v212, v64
	v_exp_f32_e32 v213, v65
	v_pk_fma_f32 v[64:65], v[76:77], s[18:19], v[152:153] op_sel_hi:[1,0,0] neg_lo:[0,0,1] neg_hi:[0,0,1]
	s_nop 0
	v_exp_f32_e32 v214, v64
	v_exp_f32_e32 v215, v65
	v_pk_fma_f32 v[64:65], v[78:79], s[18:19], v[152:153] op_sel_hi:[1,0,0] neg_lo:[0,0,1] neg_hi:[0,0,1]
	s_waitcnt lgkmcnt(2)
	s_setprio 1
	v_mfma_f32_32x32x16_bf16 v[0:15], v[182:185], v[68:71], v[0:15]
	s_setprio 0
	v_exp_f32_e32 v216, v64
	v_exp_f32_e32 v217, v65
	v_cvt_pk_bf16_f32 v182, v210, v211
	v_cvt_pk_bf16_f32 v183, v212, v213
	v_cvt_pk_bf16_f32 v184, v214, v215
	v_cvt_pk_bf16_f32 v185, v216, v217
	s_nop 1
	s_setprio 1
	v_mfma_f32_32x32x16_bf16 v[48:63], v[174:177], v[182:185], v[48:63]
	ds_read_b128 v[64:67], v170 offset:8704
	ds_read_b128 v[174:177], v170 offset:8736
	s_waitcnt lgkmcnt(1)
	v_mfma_f32_32x32x16_bf16 v[64:79], v[64:67], v[108:111], 0
	s_waitcnt lgkmcnt(0)
	v_mfma_f32_32x32x16_bf16 v[64:79], v[174:177], v[104:107], v[64:79]
	ds_read_b128 v[174:177], v170 offset:8768
	ds_read_b128 v[194:197], v170 offset:8800
	s_waitcnt lgkmcnt(1)
	v_mfma_f32_32x32x16_bf16 v[64:79], v[174:177], v[100:103], v[64:79]
	s_waitcnt lgkmcnt(0)
	v_mfma_f32_32x32x16_bf16 v[64:79], v[194:197], v[96:99], v[64:79]
	ds_read_b128 v[174:177], v170 offset:8832
	ds_read_b128 v[194:197], v170 offset:8864
	s_waitcnt lgkmcnt(1)
	v_mfma_f32_32x32x16_bf16 v[64:79], v[174:177], v[92:95], v[64:79]
	s_waitcnt lgkmcnt(0)
	v_mfma_f32_32x32x16_bf16 v[64:79], v[194:197], v[88:91], v[64:79]
	ds_read_b128 v[174:177], v170 offset:8896
	ds_read_b128 v[194:197], v170 offset:8928
	s_waitcnt lgkmcnt(1)
	v_mfma_f32_32x32x16_bf16 v[64:79], v[174:177], v[84:87], v[64:79]
	s_setprio 0
	v_add_f32_e64 v174, v204, v202
	v_add_f32_e64 v175, v205, v203
	v_add_f32_e64 v174, v206, v174
	v_add_f32_e64 v175, v207, v175
	v_pk_add_f32 v[174:175], v[208:209], v[174:175]
	s_waitcnt lgkmcnt(0)
	s_setprio 1
	v_mfma_f32_32x32x16_bf16 v[64:79], v[194:197], v[80:83], v[64:79]
	s_setprio 0
	v_add_f32_e64 v174, v210, v174
	v_add_f32_e64 v175, v211, v175
	v_add_f32_e64 v174, v212, v174
	v_add_f32_e64 v175, v213, v175
	v_add_f32_e64 v174, v214, v174
	v_add_f32_e64 v175, v215, v175
	s_nop 5
	v_max_f32_e32 v152, v64, v65
	v_max3_f32 v152, v152, v66, v67
	v_max3_f32 v152, v152, v68, v69
	v_max3_f32 v152, v152, v70, v71
	v_max3_f32 v152, v152, v72, v73
	v_max3_f32 v152, v152, v74, v75
	v_max3_f32 v152, v152, v76, v77
	v_max3_f32 v152, v152, v78, v79
	v_mov_b32_e32 v173, v152
	s_nop 1
	v_permlane32_swap_b32_e32 v173, v152
	s_setprio 1
	v_mfma_f32_32x32x16_bf16 v[32:47], v[178:181], v[182:185], v[32:47]
	s_setprio 0
	v_add_f32_e64 v174, v216, v174
	v_add_f32_e64 v175, v217, v175
	s_waitcnt lgkmcnt(0)
	v_max_f32_e32 v173, v173, v173
	v_max_f32_e32 v152, v152, v173
	v_add_f32_e32 v174, v174, v175
	v_mul_f32_e32 v152, 0x3e0293ee, v152
	s_setprio 1
	v_mfma_f32_32x32x16_bf16 v[16:31], v[186:189], v[182:185], v[16:31]
	v_add_f32_e32 v172, v172, v174
	v_add_f32_e32 v250, 0xc1000000, v152
	v_cmp_gt_f32_e32 vcc, v250, v153
	v_mfma_f32_32x32x16_bf16 v[0:15], v[190:193], v[182:185], v[0:15]
	s_setprio 0
	s_cbranch_vccnz .LBB0_1295
	v_mov_b32_e32 v152, v153
	s_branch .LBB0_1296
.LBB0_1301:
	s_barrier
	s_waitcnt vmcnt(3)
	ds_write_b128 v166, v[112:115]
	s_waitcnt vmcnt(2)
	ds_write_b128 v166, v[116:119] offset:4352
	s_waitcnt vmcnt(1)
	ds_write_b128 v166, v[120:123] offset:8704
	s_waitcnt vmcnt(0)
	ds_write_b128 v166, v[124:127] offset:13056
	ds_write_b128 v167, v[140:143] offset:17408
	ds_write_b128 v167, v[132:135] offset:22016
	ds_write_b128 v167, v[128:131] offset:26624
	ds_write_b128 v167, v[136:139] offset:31232
	s_waitcnt lgkmcnt(0)
	s_barrier
	ds_read_b128 v[64:67], v170
	ds_read_b128 v[112:115], v170 offset:32
	s_waitcnt lgkmcnt(1)
	s_setprio 1
	v_mfma_f32_32x32x16_bf16 v[64:79], v[64:67], v[108:111], 0
	s_waitcnt lgkmcnt(0)
	v_mfma_f32_32x32x16_bf16 v[64:79], v[112:115], v[104:107], v[64:79]
	ds_read_b128 v[112:115], v170 offset:64
	ds_read_b128 v[116:119], v170 offset:96
	s_waitcnt lgkmcnt(1)
	v_mfma_f32_32x32x16_bf16 v[64:79], v[112:115], v[100:103], v[64:79]
	s_waitcnt lgkmcnt(0)
	v_mfma_f32_32x32x16_bf16 v[64:79], v[116:119], v[96:99], v[64:79]
	ds_read_b128 v[112:115], v170 offset:128
	ds_read_b128 v[116:119], v170 offset:160
	s_waitcnt lgkmcnt(1)
	v_mfma_f32_32x32x16_bf16 v[64:79], v[112:115], v[92:95], v[64:79]
	s_waitcnt lgkmcnt(0)
	v_mfma_f32_32x32x16_bf16 v[64:79], v[116:119], v[88:91], v[64:79]
	ds_read_b128 v[112:115], v170 offset:192
	ds_read_b128 v[116:119], v170 offset:224
	s_waitcnt lgkmcnt(1)
	v_mfma_f32_32x32x16_bf16 v[64:79], v[112:115], v[84:87], v[64:79]
	s_waitcnt lgkmcnt(0)
	v_mfma_f32_32x32x16_bf16 v[64:79], v[116:119], v[80:83], v[64:79]
	s_setprio 0
	s_nop 11
	v_max_f32_e32 v112, v64, v65
	v_max3_f32 v112, v112, v66, v67
	v_max3_f32 v112, v112, v68, v69
	v_max3_f32 v112, v112, v70, v71
	v_max3_f32 v112, v112, v72, v73
	v_max3_f32 v112, v112, v74, v75
	v_max3_f32 v112, v112, v76, v77
	v_max3_f32 v112, v112, v78, v79
	v_mov_b32_e32 v113, v112
	s_nop 1
	v_permlane32_swap_b32_e32 v113, v112
	s_waitcnt lgkmcnt(0)
	v_max_f32_e32 v112, v112, v113
	v_mul_f32_e32 v112, 0x3e0293ee, v112
	v_add_f32_e32 v250, 0xc1000000, v112
	v_cmp_gt_f32_e32 vcc, v250, v153
	s_cbranch_vccz .LBB0_1303
	v_max_f32_e32 v112, v112, v112
	v_max_f32_e32 v113, v153, v153
	v_max_f32_e32 v152, v113, v112
	v_sub_f32_e32 v112, v153, v152
	v_exp_f32_e32 v112, v112
	v_mov_b32_e32 v153, v152
	v_pk_mul_f32 v[62:63], v[62:63], v[112:113] op_sel_hi:[1,0]
	v_pk_mul_f32 v[60:61], v[60:61], v[112:113] op_sel_hi:[1,0]
	v_pk_mul_f32 v[58:59], v[58:59], v[112:113] op_sel_hi:[1,0]
	v_pk_mul_f32 v[56:57], v[56:57], v[112:113] op_sel_hi:[1,0]
	v_pk_mul_f32 v[54:55], v[54:55], v[112:113] op_sel_hi:[1,0]
	v_pk_mul_f32 v[52:53], v[52:53], v[112:113] op_sel_hi:[1,0]
	v_pk_mul_f32 v[50:51], v[50:51], v[112:113] op_sel_hi:[1,0]
	v_pk_mul_f32 v[48:49], v[48:49], v[112:113] op_sel_hi:[1,0]
	v_pk_mul_f32 v[46:47], v[46:47], v[112:113] op_sel_hi:[1,0]
	v_pk_mul_f32 v[44:45], v[44:45], v[112:113] op_sel_hi:[1,0]
	v_pk_mul_f32 v[42:43], v[42:43], v[112:113] op_sel_hi:[1,0]
	v_pk_mul_f32 v[40:41], v[40:41], v[112:113] op_sel_hi:[1,0]
	v_pk_mul_f32 v[38:39], v[38:39], v[112:113] op_sel_hi:[1,0]
	v_pk_mul_f32 v[36:37], v[36:37], v[112:113] op_sel_hi:[1,0]
	v_pk_mul_f32 v[34:35], v[34:35], v[112:113] op_sel_hi:[1,0]
	v_pk_mul_f32 v[32:33], v[32:33], v[112:113] op_sel_hi:[1,0]
	v_pk_mul_f32 v[30:31], v[30:31], v[112:113] op_sel_hi:[1,0]
	v_pk_mul_f32 v[28:29], v[28:29], v[112:113] op_sel_hi:[1,0]
	v_pk_mul_f32 v[26:27], v[26:27], v[112:113] op_sel_hi:[1,0]
	v_pk_mul_f32 v[24:25], v[24:25], v[112:113] op_sel_hi:[1,0]
	v_pk_mul_f32 v[22:23], v[22:23], v[112:113] op_sel_hi:[1,0]
	v_pk_mul_f32 v[20:21], v[20:21], v[112:113] op_sel_hi:[1,0]
	v_pk_mul_f32 v[18:19], v[18:19], v[112:113] op_sel_hi:[1,0]
	v_pk_mul_f32 v[16:17], v[16:17], v[112:113] op_sel_hi:[1,0]
	v_pk_mul_f32 v[14:15], v[14:15], v[112:113] op_sel_hi:[1,0]
	v_pk_mul_f32 v[12:13], v[12:13], v[112:113] op_sel_hi:[1,0]
	v_pk_mul_f32 v[10:11], v[10:11], v[112:113] op_sel_hi:[1,0]
	v_pk_mul_f32 v[8:9], v[8:9], v[112:113] op_sel_hi:[1,0]
	v_pk_mul_f32 v[6:7], v[6:7], v[112:113] op_sel_hi:[1,0]
	v_pk_mul_f32 v[4:5], v[4:5], v[112:113] op_sel_hi:[1,0]
	v_pk_mul_f32 v[2:3], v[2:3], v[112:113] op_sel_hi:[1,0]
	v_pk_mul_f32 v[0:1], v[0:1], v[112:113] op_sel_hi:[1,0]
	v_mul_f32_e32 v172, v172, v112
	v_mov_b32_e32 v112, v152
	s_branch .LBB0_1304

.LBB0_1304:
	v_pk_fma_f32 v[64:65], v[64:65], s[18:19], v[152:153] op_sel_hi:[1,0,1] neg_lo:[0,0,1] neg_hi:[0,0,1]
	v_pk_fma_f32 v[72:73], v[72:73], s[18:19], v[152:153] op_sel_hi:[1,0,1] neg_lo:[0,0,1] neg_hi:[0,0,1]
	v_exp_f32_e32 v134, v64
	v_exp_f32_e32 v135, v65
	v_pk_fma_f32 v[64:65], v[66:67], s[18:19], v[152:153] op_sel_hi:[1,0,1] neg_lo:[0,0,1] neg_hi:[0,0,1]
	ds_read_b128 v[114:117], v171 offset:17440
	v_exp_f32_e32 v136, v64
	v_exp_f32_e32 v137, v65
	v_pk_fma_f32 v[64:65], v[68:69], s[18:19], v[152:153] op_sel_hi:[1,0,1] neg_lo:[0,0,1] neg_hi:[0,0,1]
	v_pk_fma_f32 v[68:69], v[70:71], s[18:19], v[152:153] op_sel_hi:[1,0,1] neg_lo:[0,0,1] neg_hi:[0,0,1]
	v_exp_f32_e32 v138, v64
	v_exp_f32_e32 v139, v65
	ds_read_b128 v[64:67], v171 offset:17408
	v_exp_f32_e32 v140, v68
	v_exp_f32_e32 v141, v69
	v_cvt_pk_bf16_f32 v68, v134, v135
	v_cvt_pk_bf16_f32 v69, v136, v137
	v_cvt_pk_bf16_f32 v70, v138, v139
	v_cvt_pk_bf16_f32 v71, v140, v141
	v_exp_f32_e32 v142, v72
	v_exp_f32_e32 v143, v73
	s_waitcnt lgkmcnt(0)
	s_setprio 1
	v_mfma_f32_32x32x16_bf16 v[48:63], v[64:67], v[68:71], v[48:63]
	ds_read_b128 v[64:67], v171 offset:22016
	ds_read_b128 v[118:121], v171 offset:22048
	s_waitcnt lgkmcnt(1)
	v_mfma_f32_32x32x16_bf16 v[32:47], v[64:67], v[68:71], v[32:47]
	ds_read_b128 v[64:67], v171 offset:26624
	ds_read_b128 v[122:125], v171 offset:31232
	ds_read_b128 v[126:129], v171 offset:26656
	ds_read_b128 v[130:133], v171 offset:31264
	s_waitcnt lgkmcnt(3)
	v_mfma_f32_32x32x16_bf16 v[16:31], v[64:67], v[68:71], v[16:31]
	s_setprio 0
	v_fma_f32 v64, v74, s18, -v152
	v_fma_f32 v65, v75, s18, -v153
	v_exp_f32_e32 v154, v64
	v_exp_f32_e32 v155, v65
	v_pk_fma_f32 v[64:65], v[76:77], s[18:19], v[152:153] op_sel_hi:[1,0,1] neg_lo:[0,0,1] neg_hi:[0,0,1]
	s_nop 0
	v_exp_f32_e32 v156, v64
	v_exp_f32_e32 v157, v65
	v_pk_fma_f32 v[64:65], v[78:79], s[18:19], v[152:153] op_sel_hi:[1,0,1] neg_lo:[0,0,1] neg_hi:[0,0,1]
	s_waitcnt lgkmcnt(2)
	s_setprio 1
	v_mfma_f32_32x32x16_bf16 v[0:15], v[122:125], v[68:71], v[0:15]
	s_setprio 0
	v_exp_f32_e32 v158, v64
	v_exp_f32_e32 v159, v65
	v_cvt_pk_bf16_f32 v122, v142, v143
	v_cvt_pk_bf16_f32 v123, v154, v155
	v_cvt_pk_bf16_f32 v124, v156, v157
	v_cvt_pk_bf16_f32 v125, v158, v159
	s_nop 1
	s_setprio 1
	v_mfma_f32_32x32x16_bf16 v[48:63], v[114:117], v[122:125], v[48:63]
	ds_read_b128 v[64:67], v170 offset:8704
	ds_read_b128 v[114:117], v170 offset:8736
	s_waitcnt lgkmcnt(1)
	v_mfma_f32_32x32x16_bf16 v[64:79], v[64:67], v[108:111], 0
	s_waitcnt lgkmcnt(0)
	v_mfma_f32_32x32x16_bf16 v[64:79], v[114:117], v[104:107], v[64:79]
	ds_read_b128 v[104:107], v170 offset:8768
	ds_read_b128 v[108:111], v170 offset:8800
	s_waitcnt lgkmcnt(1)
	v_mfma_f32_32x32x16_bf16 v[64:79], v[104:107], v[100:103], v[64:79]
	s_waitcnt lgkmcnt(0)
	v_mfma_f32_32x32x16_bf16 v[64:79], v[108:111], v[96:99], v[64:79]
	ds_read_b128 v[96:99], v170 offset:8832
	ds_read_b128 v[100:103], v170 offset:8864
	s_waitcnt lgkmcnt(1)
	v_mfma_f32_32x32x16_bf16 v[64:79], v[96:99], v[92:95], v[64:79]
	s_waitcnt lgkmcnt(0)
	v_mfma_f32_32x32x16_bf16 v[64:79], v[100:103], v[88:91], v[64:79]
	ds_read_b128 v[88:91], v170 offset:8896
	ds_read_b128 v[92:95], v170 offset:8928
	s_waitcnt lgkmcnt(1)
	v_mfma_f32_32x32x16_bf16 v[64:79], v[88:91], v[84:87], v[64:79]
	s_setprio 0
	v_add_f32_e64 v84, v136, v134
	v_add_f32_e64 v85, v137, v135
	v_add_f32_e64 v84, v138, v84
	v_add_f32_e64 v85, v139, v85
	v_pk_add_f32 v[84:85], v[140:141], v[84:85]
	s_waitcnt lgkmcnt(0)
	s_setprio 1
	v_mfma_f32_32x32x16_bf16 v[64:79], v[92:95], v[80:83], v[64:79]
	s_setprio 0
	v_add_f32_e64 v80, v142, v84
	v_add_f32_e64 v81, v143, v85
	v_add_f32_e64 v80, v154, v80
	v_add_f32_e64 v81, v155, v81
	v_add_f32_e64 v80, v156, v80
	v_add_f32_e64 v81, v157, v81
	s_nop 5
	v_max_f32_e32 v82, v64, v65
	v_max3_f32 v82, v82, v66, v67
	v_max3_f32 v82, v82, v68, v69
	v_max3_f32 v82, v82, v70, v71
	v_max3_f32 v82, v82, v72, v73
	v_max3_f32 v82, v82, v74, v75
	v_max3_f32 v82, v82, v76, v77
	v_max3_f32 v82, v82, v78, v79
	ds_bpermute_b32 v83, v168, v82
	s_setprio 1
	v_mfma_f32_32x32x16_bf16 v[32:47], v[118:121], v[122:125], v[32:47]
	s_setprio 0
	v_add_f32_e64 v80, v158, v80
	v_add_f32_e64 v81, v159, v81
	v_add_f32_e32 v80, v80, v81
	s_waitcnt lgkmcnt(0)
	v_max_f32_e32 v81, v83, v83
	v_max_f32_e32 v81, v82, v81
	v_mul_f32_e32 v81, 0x3e0293ee, v81
	v_add_f32_e32 v80, v172, v80
	s_setprio 1
	v_mfma_f32_32x32x16_bf16 v[16:31], v[126:129], v[122:125], v[16:31]
	v_add_f32_e32 v250, 0xc1000000, v81
	v_cmp_gt_f32_e32 vcc, v250, v112
	v_mfma_f32_32x32x16_bf16 v[0:15], v[130:133], v[122:125], v[0:15]
	s_setprio 0
	s_cbranch_vccz .LBB0_1285
	v_max_f32_e32 v81, v81, v81
	v_max_f32_e32 v82, v112, v112
	v_max_f32_e32 v152, v82, v81
	v_sub_f32_e32 v81, v112, v152
	v_exp_f32_e32 v82, v81
	v_mov_b32_e32 v153, v152
	v_pk_mul_f32 v[62:63], v[62:63], v[82:83] op_sel_hi:[1,0]
	v_pk_mul_f32 v[60:61], v[60:61], v[82:83] op_sel_hi:[1,0]
	v_pk_mul_f32 v[58:59], v[58:59], v[82:83] op_sel_hi:[1,0]
	v_pk_mul_f32 v[56:57], v[56:57], v[82:83] op_sel_hi:[1,0]
	v_pk_mul_f32 v[54:55], v[54:55], v[82:83] op_sel_hi:[1,0]
	v_pk_mul_f32 v[52:53], v[52:53], v[82:83] op_sel_hi:[1,0]
	v_pk_mul_f32 v[50:51], v[50:51], v[82:83] op_sel_hi:[1,0]
	v_pk_mul_f32 v[48:49], v[48:49], v[82:83] op_sel_hi:[1,0]
	v_pk_mul_f32 v[46:47], v[46:47], v[82:83] op_sel_hi:[1,0]
	v_pk_mul_f32 v[44:45], v[44:45], v[82:83] op_sel_hi:[1,0]
	v_pk_mul_f32 v[42:43], v[42:43], v[82:83] op_sel_hi:[1,0]
	v_pk_mul_f32 v[40:41], v[40:41], v[82:83] op_sel_hi:[1,0]
	v_pk_mul_f32 v[38:39], v[38:39], v[82:83] op_sel_hi:[1,0]
	v_pk_mul_f32 v[36:37], v[36:37], v[82:83] op_sel_hi:[1,0]
	v_pk_mul_f32 v[34:35], v[34:35], v[82:83] op_sel_hi:[1,0]
	v_pk_mul_f32 v[32:33], v[32:33], v[82:83] op_sel_hi:[1,0]
	v_pk_mul_f32 v[30:31], v[30:31], v[82:83] op_sel_hi:[1,0]
	v_pk_mul_f32 v[28:29], v[28:29], v[82:83] op_sel_hi:[1,0]
	v_pk_mul_f32 v[26:27], v[26:27], v[82:83] op_sel_hi:[1,0]
	v_pk_mul_f32 v[24:25], v[24:25], v[82:83] op_sel_hi:[1,0]
	v_pk_mul_f32 v[22:23], v[22:23], v[82:83] op_sel_hi:[1,0]
	v_pk_mul_f32 v[20:21], v[20:21], v[82:83] op_sel_hi:[1,0]
	v_pk_mul_f32 v[18:19], v[18:19], v[82:83] op_sel_hi:[1,0]
	v_pk_mul_f32 v[16:17], v[16:17], v[82:83] op_sel_hi:[1,0]
	v_pk_mul_f32 v[14:15], v[14:15], v[82:83] op_sel_hi:[1,0]
	v_pk_mul_f32 v[12:13], v[12:13], v[82:83] op_sel_hi:[1,0]
	v_pk_mul_f32 v[10:11], v[10:11], v[82:83] op_sel_hi:[1,0]
	v_pk_mul_f32 v[8:9], v[8:9], v[82:83] op_sel_hi:[1,0]
	v_pk_mul_f32 v[6:7], v[6:7], v[82:83] op_sel_hi:[1,0]
	v_pk_mul_f32 v[4:5], v[4:5], v[82:83] op_sel_hi:[1,0]
	v_pk_mul_f32 v[2:3], v[2:3], v[82:83] op_sel_hi:[1,0]
	v_pk_mul_f32 v[0:1], v[0:1], v[82:83] op_sel_hi:[1,0]
	v_mul_f32_e32 v80, v80, v82
	s_branch .LBB0_1285
